# VW
# speedup vs baseline: 1.0343x; 1.0045x over previous
; template <int MODE> ...
;   int tid = threadIdx.x;
;   asm volatile("" : "+v"(tid));
;   const int lane = tid & 63, c = lane & 15, quad = lane >> 4;
;   float m_run[2] = {-1e30f, -1e30f}, l_run[2] = {0.f, 0.f};
; #pragma unroll
;   for (int qs = 0; qs < 2; ++qs)
; #pragma unroll
;     for (int i = 0; i < 8; ++i) o[qs][i] = (f32x4){0.f, 0.f, 0.f, 0.f};
;   const int krow0 = tid >> 4, kch = tid & 15;
;   const int vrow0 = tid >> 3, vch = tid & 7;
;   const bf16_t* kp = Kg + (size_t)(jlo * 64 + krow0) * NPAD + kch * 8;
;   const bf16_t* vp0 = VTg + (size_t)vrow0 * SEQ + jlo * 64 + vch * 8;
;   uint4 kr0 = *(const uint4*)kp, kr1 = *(const uint4*)(kp + (size_t)32 * NPAD);
;   uint4 vr0 = *(const uint4*)vp0, vr1 = *(const uint4*)(vp0 + (size_t)64 * SEQ);
;   __syncthreads();
;   stage_write_k((bf16_t*)smem, krow0, kch, kr0, kr1);
;   stage_write_v((bf16_t*)(smem + KT_BYTES), vrow0, vch, vr0, vr1);
;   __syncthreads();
; __device__ __forceinline__ void attn_phase(const bf16_t* __restrict__ proj, const bf16_t* __restrict__ KC,
;                            const bf16_t* __restrict__ VCT, const bf16_t* __restrict__ VT,
;                            bf16_t* __restrict__ mixed) {
;     ...
;     bf16x8 qf[2][4];
; #pragma unroll
;     for (int qs = 0; qs < 2; ++qs) {
;       const bf16_t* qp = proj + (row0 + qs * 4) * NPAD + OFF_Q + head * 128 + quad * 8;
; #pragma unroll
;       for (int ks = 0; ks < 4; ++ks) qf[qs][ks] = *(const bf16x8*)(qp + ks * 32);
;     }
;     const int cur_blk = ttile;
;     {
;       f32x4 o[2][8];
;       float l[2];
;       const bf16_t* Kg = proj + (size_t)b * SEQ * NPAD + OFF_KS + g * 128;
;       const bf16_t* VTg = VT + (size_t)((0 * 2 + b) * 4 + g) * 128 * SEQ;
;       flash_loop2<0>(Kg, VTg, 0, cur_blk, qf, tok, mymask, wunion, o, l, smem_raw);
.LBB0_319:
	v_mov_b64_e32 v[0:1], s[36:37]
	v_mad_u64_u32 v[192:193], s[8:9], v184, s81, v[0:1]
	v_mad_i32_i24 v193, v185, s81, v193
	s_mul_i32 s8, s34, 0x7a00
	v_mov_b32_e32 v105, v181
	v_lshl_add_u64 v[0:1], v[192:193], 0, v[180:181]
	s_add_u32 s25, s36, s8
	v_lshl_add_u64 v[16:17], v[0:1], 0, v[104:105]
	s_addc_u32 s60, s37, 0
	s_lshl_b32 s9, s24, 8
	v_add_co_u32_e32 v8, vcc, s47, v16
	s_add_u32 s10, s25, s9
	s_nop 0
	v_addc_co_u32_e32 v9, vcc, 0, v17, vcc
	s_addc_u32 s11, s60, 0
	v_add_co_u32_e32 v24, vcc, s85, v16
	s_add_u32 s10, s10, 0x5800
	v_lshl_add_u64 v[12:13], v[16:17], 0, s[40:41]
	v_lshl_add_u64 v[28:29], v[16:17], 0, s[44:45]
	v_addc_co_u32_e32 v25, vcc, 0, v17, vcc
	s_addc_u32 s11, s11, 0
	s_lshl_b32 s12, s95, 20
	v_mov_b32_e32 v39, v254
	global_load_dwordx4 v[0:3], v[12:13], off offset:64
	global_load_dwordx4 v[4:7], v[12:13], off offset:128
	s_nop 0
	global_load_dwordx4 v[8:11], v[8:9], off
	s_nop 0
	global_load_dwordx4 v[12:15], v[12:13], off offset:192
	s_nop 0
	global_load_dwordx4 v[16:19], v[28:29], off offset:64
	global_load_dwordx4 v[20:23], v[28:29], off offset:128
	s_nop 0
	global_load_dwordx4 v[24:27], v[24:25], off offset:2048
	s_nop 0
	global_load_dwordx4 v[28:31], v[28:29], off offset:192
	s_and_b32 s12, s12, 0x700000
	v_mov_b64_e32 v[32:33], s[10:11]
	v_and_b32_e32 v172, 15, v39
	v_ashrrev_i32_e32 v38, 4, v39
	v_ashrrev_i32_e32 v56, 3, v39
	s_add_u32 s14, s75, s12
	v_mad_i64_i32 v[34:35], s[10:11], v38, s81, v[32:33]
	v_lshlrev_b32_e32 v32, 4, v172
	v_mov_b32_e32 v33, v181
	v_ashrrev_i32_e32 v57, 31, v56
	s_addc_u32 s15, s76, 0
	v_and_b32_e32 v36, 7, v39
	v_lshl_add_u64 v[48:49], v[34:35], 0, v[32:33]
	v_lshlrev_b64 v[34:35], 13, v[56:57]
	v_lshl_add_u64 v[40:41], s[14:15], 0, v[34:35]
	v_lshlrev_b32_e32 v36, 4, v36
	v_mov_b32_e32 v37, v181
	v_lshl_add_u64 v[52:53], v[40:41], 0, v[36:37]
	global_load_dwordx4 v[40:43], v[52:53], off
	global_load_dwordx4 v[44:47], v[48:49], off
	v_add_co_u32_e32 v48, vcc, s89, v48
	v_bfe_u32 v170, v39, 4, 2
	s_nop 0
	v_addc_co_u32_e32 v49, vcc, 0, v49, vcc
	global_load_dwordx4 v[48:51], v[48:49], off
	v_add_co_u32_e32 v52, vcc, s88, v52
	v_lshlrev_b32_e32 v57, 3, v39
	s_nop 0
	v_addc_co_u32_e32 v53, vcc, 0, v53, vcc
	global_load_dwordx4 v[52:55], v[52:53], off
	v_lshlrev_b32_e32 v58, 4, v39
	v_lshlrev_b32_e32 v39, 1, v39
	v_and_b32_e32 v57, 32, v57
	v_and_b32_e32 v58, 16, v58
	v_and_b32_e32 v39, 4, v39
	v_mul_lo_u32 v59, v38, s86
	v_mul_lo_u32 v56, v56, s87
	v_or3_b32 v39, v57, v58, v39
	v_lshlrev_b32_e32 v173, 1, v59
	v_lshlrev_b32_e32 v174, 1, v56
	v_lshlrev_b32_e32 v175, 1, v39
	v_add3_u32 v56, 16, v173, v32
	v_add3_u32 v39, 16, v174, v175
	s_cmp_lg_u32 s96, 0
	v_lshlrev_b32_e32 v171, 4, v170
	v_add_u32_e32 v57, 0x4000, v39
	v_add_u32_e32 v39, 0x6800, v39
	s_barrier
	s_waitcnt vmcnt(2)
	ds_write_b128 v56, v[44:47]
	s_waitcnt vmcnt(1)
	ds_write_b128 v56, v[48:51] offset:8704
	ds_write2_b64 v57, v[40:41], v[42:43] offset0:128 offset1:130
	s_waitcnt vmcnt(0)
	ds_write2_b64 v39, v[52:53], v[54:55] offset1:2
	s_waitcnt lgkmcnt(0)
	s_barrier
	s_cbranch_scc0 .LBB0_327
	s_add_u32 s8, s9, s8
	v_mad_i64_i32 v[38:39], s[10:11], v38, s81, 0
	s_addc_u32 s9, 0, 0
	v_lshl_add_u64 v[38:39], s[8:9], 0, v[38:39]
	s_and_b32 s8, s95, 7
	s_lshl_b32 s34, s8, 20
	v_lshlrev_b32_e32 v40, 3, v172
	v_lshl_add_u64 v[144:145], v[38:39], 0, v[32:33]
	v_lshl_add_u64 v[32:33], s[34:35], 0, v[34:35]
	v_mov_b32_e32 v48, v181
	v_mov_b32_e32 v49, v181
	v_mov_b32_e32 v50, v181
	v_mov_b32_e32 v51, v181
	v_lshl_add_u64 v[146:147], v[32:33], 0, v[36:37]
	v_mov_b32_e32 v164, 0xf149f2ca
	v_lshlrev_b32_e32 v179, 1, v40
	v_mov_b64_e32 v[32:33], v[48:49]
	v_mov_b64_e32 v[40:41], v[48:49]
	v_mov_b64_e32 v[54:55], v[50:51]
	v_mov_b64_e32 v[66:67], v[50:51]
	v_mov_b64_e32 v[74:75], v[50:51]
	v_mov_b64_e32 v[82:83], v[50:51]
	v_mov_b64_e32 v[90:91], v[50:51]
	v_mov_b64_e32 v[62:63], v[50:51]
	v_mov_b64_e32 v[36:37], v[48:49]
	v_mov_b64_e32 v[44:45], v[48:49]
	v_mov_b64_e32 v[58:59], v[50:51]
	v_mov_b64_e32 v[70:71], v[50:51]
	v_mov_b64_e32 v[78:79], v[50:51]
	v_mov_b64_e32 v[86:87], v[50:51]
	v_mov_b64_e32 v[94:95], v[50:51]
	v_mul_u32_u24_e32 v176, 0x110, v172
	v_mul_u32_u24_e32 v177, 0x90, v172
	v_add_u32_e32 v178, 16, v171
	v_mov_b32_e32 v194, v181
	v_mov_b32_e32 v195, v181
	s_mov_b64 s[58:59], 0
	v_mov_b64_e32 v[34:35], v[50:51]
	v_mov_b64_e32 v[42:43], v[50:51]
	v_mov_b64_e32 v[52:53], v[48:49]
	v_mov_b64_e32 v[64:65], v[48:49]
	v_mov_b64_e32 v[72:73], v[48:49]
	v_mov_b64_e32 v[80:81], v[48:49]
	v_mov_b64_e32 v[88:89], v[48:49]
	v_mov_b64_e32 v[60:61], v[48:49]
	v_mov_b64_e32 v[38:39], v[50:51]
	v_mov_b64_e32 v[46:47], v[50:51]
	v_mov_b64_e32 v[56:57], v[48:49]
	v_mov_b64_e32 v[68:69], v[48:49]
	v_mov_b64_e32 v[76:77], v[48:49]
	v_mov_b64_e32 v[84:85], v[48:49]
	v_mov_b64_e32 v[92:93], v[48:49]
	v_mov_b32_e32 v165, v164
	v_lshl_add_u64 v[144:145], s[30:31], 0, v[144:145]
	v_lshl_add_u64 v[146:147], s[30:31], 0, v[146:147]
	v_add_co_u32_e32 v144, vcc, s90, v144
	s_nop 1
	v_addc_co_u32_e32 v145, vcc, 0, v145, vcc
	v_add_co_u32_e32 v146, vcc, 0x3a800000, v146
	s_nop 1
	v_addc_co_u32_e32 v147, vcc, 0, v147, vcc
	s_branch .LBB0_323

.LBB0_323:
	v_add_co_u32_e32 v100, vcc, 0xf4000, v144
	s_lshl_b64 s[8:9], 1, s58
	global_load_dwordx4 v[96:99], v[144:145], off offset:2048
	v_addc_co_u32_e32 v101, vcc, 0, v145, vcc
	v_add_co_u32_e32 v108, vcc, 0x80000, v146
	s_and_b32 s34, s58, 1
	global_load_dwordx4 v[100:103], v[100:101], off offset:2048
	v_addc_co_u32_e32 v109, vcc, 0, v147, vcc
	global_load_dwordx4 v[104:107], v[146:147], off offset:128
	global_load_dwordx4 v[108:111], v[108:109], off offset:128
	s_and_b64 s[10:11], s[8:9], s[16:17]
	s_cmp_eq_u64 s[10:11], 0
	s_cbranch_scc1 .LBB0_322
	s_mul_i32 s10, s34, 0x8c00
	v_add_u32_e32 v167, s10, v178
	v_add_u32_e32 v166, v167, v176
	ds_read_b128 v[112:115], v166
	ds_read_b128 v[116:119], v166 offset:64
	ds_read_b128 v[124:127], v166 offset:4352
	ds_read_b128 v[132:135], v166 offset:4416
	v_and_b32_e32 v169, s9, v163
	v_and_b32_e32 v168, s8, v162
	s_waitcnt lgkmcnt(3)
	v_mfma_f32_16x16x32_bf16 v[120:123], v[112:115], v[8:11], 0
	v_cmp_eq_u64_e64 s[10:11], 0, v[168:169]
	s_waitcnt lgkmcnt(1)
	v_mfma_f32_16x16x32_bf16 v[128:131], v[124:127], v[8:11], 0
	v_mfma_f32_16x16x32_bf16 v[136:139], v[124:127], v[24:27], 0
	ds_read_b128 v[124:127], v166 offset:8704
	ds_read_b128 v[148:151], v166 offset:8768
	ds_read_b128 v[156:159], v166 offset:13056
	ds_read_b128 v[196:199], v166 offset:13120
	ds_read_b128 v[204:207], v166 offset:128
	ds_read_b128 v[218:221], v166 offset:192
	v_mfma_f32_16x16x32_bf16 v[120:123], v[116:119], v[0:3], v[120:123]
	ds_read_b128 v[222:225], v166 offset:4480
	ds_read_b128 v[226:229], v166 offset:4544
	ds_read_b128 v[230:233], v166 offset:8832
	ds_read_b128 v[234:237], v166 offset:8896
	ds_read_b128 v[242:245], v166 offset:13184
	ds_read_b128 v[246:249], v166 offset:13248
	s_waitcnt lgkmcnt(11)
	v_mfma_f32_16x16x32_bf16 v[140:143], v[124:127], v[8:11], 0
	v_mfma_f32_16x16x32_bf16 v[152:155], v[124:127], v[24:27], 0
	s_waitcnt lgkmcnt(9)
	v_mfma_f32_16x16x32_bf16 v[124:127], v[156:159], v[8:11], 0
	v_mfma_f32_16x16x32_bf16 v[128:131], v[132:135], v[0:3], v[128:131]
	s_waitcnt lgkmcnt(7)
	v_mfma_f32_16x16x32_bf16 v[120:123], v[204:207], v[4:7], v[120:123]
	v_mfma_f32_16x16x32_bf16 v[140:143], v[148:151], v[0:3], v[140:143]
	v_mfma_f32_16x16x32_bf16 v[200:203], v[196:199], v[0:3], v[124:127]
	s_waitcnt lgkmcnt(5)
	v_mfma_f32_16x16x32_bf16 v[124:127], v[222:225], v[4:7], v[128:131]
	v_mfma_f32_16x16x32_bf16 v[128:131], v[218:221], v[12:15], v[120:123]
	s_waitcnt lgkmcnt(3)
	v_mfma_f32_16x16x32_bf16 v[238:241], v[230:233], v[4:7], v[140:143]
	v_mfma_f32_16x16x32_bf16 v[140:143], v[226:229], v[12:15], v[124:127]
	s_nop 4
	v_max_f32_e32 v120, v130, v131
	v_max3_f32 v166, v128, v129, v120
	s_waitcnt lgkmcnt(2)
	v_mfma_f32_16x16x32_bf16 v[124:127], v[234:237], v[12:15], v[238:241]
	v_max_f32_e32 v120, v142, v143
	v_max3_f32 v183, v140, v141, v120
	s_waitcnt lgkmcnt(1)
	v_mfma_f32_16x16x32_bf16 v[120:123], v[242:245], v[4:7], v[200:203]
	s_nop 1
	s_waitcnt lgkmcnt(0)
	v_mfma_f32_16x16x32_bf16 v[120:123], v[246:249], v[12:15], v[120:123]
	v_max_f32_e32 v191, v124, v125
	v_mfma_f32_16x16x32_bf16 v[112:115], v[112:115], v[24:27], 0
	v_max_f32_e32 v200, v126, v127
	s_nop 1
	s_nop 2
	v_max_f32_e32 v202, v122, v122
	v_max_f32_e32 v201, v202, v123
	v_max3_f32 v201, v120, v121, v201
	v_mfma_f32_16x16x32_bf16 v[112:115], v[116:119], v[16:19], v[112:115]
	v_max3_f32 v116, v191, v200, v201
	v_max3_f32 v116, v166, v183, v116
	v_mul_f32_e32 v166, 0x3e0293ee, v116
	v_mfma_f32_16x16x32_bf16 v[116:119], v[132:135], v[16:19], v[136:139]
	v_cndmask_b32_e64 v132, v166, v214, s[10:11]
	v_mov_b32_e32 v133, v132
	s_nop 1
	v_permlane16_swap_b32_e32 v132, v133
	v_mfma_f32_16x16x32_bf16 v[112:115], v[204:207], v[20:23], v[112:115]
	v_max_f32_e32 v132, v132, v133
	v_mfma_f32_16x16x32_bf16 v[156:159], v[156:159], v[24:27], 0
	v_mov_b32_e32 v133, v132
	s_nop 1
	v_permlane32_swap_b32_e32 v132, v133
	v_mfma_f32_16x16x32_bf16 v[116:119], v[222:225], v[20:23], v[116:119]
	v_mfma_f32_16x16x32_bf16 v[136:139], v[218:221], v[28:31], v[112:115]
	v_mfma_f32_16x16x32_bf16 v[148:151], v[148:151], v[16:19], v[152:155]
	v_mfma_f32_16x16x32_bf16 v[152:155], v[196:199], v[16:19], v[156:159]
	s_nop 5
	v_max_f32_e32 v112, v138, v139
	v_max_f32_e32 v158, v132, v133
	v_mfma_f32_16x16x32_bf16 v[132:135], v[226:229], v[28:31], v[116:119]
	v_max3_f32 v159, v136, v137, v112
	v_and_b32_e32 v157, s9, v161
	v_and_b32_e32 v156, s8, v160
	v_mfma_f32_16x16x32_bf16 v[112:115], v[230:233], v[20:23], v[148:151]
	v_cmp_eq_u64_e64 s[8:9], 0, v[156:157]
	s_nop 2
	v_max_f32_e32 v116, v134, v135
	v_max3_f32 v148, v132, v133, v116
	v_mfma_f32_16x16x32_bf16 v[116:119], v[234:237], v[28:31], v[112:115]
	s_nop 7
	v_max_f32_e32 v149, v116, v117
	v_mfma_f32_16x16x32_bf16 v[112:115], v[242:245], v[20:23], v[152:155]
	v_max_f32_e32 v150, v118, v119
	v_mfma_f32_16x16x32_bf16 v[112:115], v[246:249], v[28:31], v[112:115]
	s_nop 7
	v_max_f32_e32 v152, v114, v114
	v_max_f32_e32 v151, v152, v115
	v_max3_f32 v151, v112, v113, v151
	v_max3_f32 v149, v149, v150, v151
	v_max3_f32 v148, v159, v148, v149
	v_mul_f32_e32 v148, 0x3e0293ee, v148
	v_cndmask_b32_e64 v148, v148, v214, s[8:9]
	v_mov_b32_e32 v149, v148
	s_nop 1
	v_permlane16_swap_b32_e32 v148, v149
	v_max_f32_e32 v148, v148, v149
	v_mov_b32_e32 v149, v148
	s_nop 1
	v_permlane32_swap_b32_e32 v148, v149
	v_max_f32_e32 v150, v148, v149
	v_pk_add_f32 v[148:149], v[164:165], s[46:47] op_sel_hi:[1,0]
	s_nop 0
	v_cmp_gt_f32_e32 vcc, v150, v149
	s_nop 1
	v_cndmask_b32_e32 v149, v165, v150, vcc
	v_cmp_gt_f32_e32 vcc, v158, v148
	s_nop 1
	v_cndmask_b32_e32 v148, v164, v158, vcc
	v_pk_add_f32 v[150:151], v[164:165], v[148:149] neg_lo:[0,1] neg_hi:[0,1]
	s_nop 0
	v_exp_f32_e32 v150, v150
	v_exp_f32_e32 v151, v151
	v_cmp_neq_f32_e32 vcc, 1.0, v150
	v_cmp_neq_f32_e64 s[12:13], 1.0, v151
	s_or_b64 vcc, vcc, s[12:13]
	s_cbranch_vccz .LBB0_321
; template <int MODE> ...
;     ...
;       if (__ballot(alpha[0] != 1.0f || alpha[1] != 1.0f) != 0ull) {
; #pragma unroll
;         for (int qs = 0; qs < 2; ++qs)
; #pragma unroll
;           for (int dt = 0; dt < 8; ++dt) {
;             o[qs][dt][0] *= alpha[qs]; o[qs][dt][1] *= alpha[qs]; o[qs][dt][2] *= alpha[qs]; o[qs][dt][3] *= alpha[qs];
;           }
;       }
	v_mov_b32_e32 v152, v151
	v_pk_mul_f32 v[92:93], v[92:93], v[150:151] op_sel_hi:[1,0]
	v_pk_mul_f32 v[94:95], v[94:95], v[150:151] op_sel_hi:[1,0]
	v_pk_mul_f32 v[84:85], v[84:85], v[150:151] op_sel_hi:[1,0]
	v_pk_mul_f32 v[86:87], v[86:87], v[150:151] op_sel_hi:[1,0]
	v_pk_mul_f32 v[76:77], v[76:77], v[150:151] op_sel_hi:[1,0]
	v_pk_mul_f32 v[78:79], v[78:79], v[150:151] op_sel_hi:[1,0]
	v_pk_mul_f32 v[68:69], v[68:69], v[150:151] op_sel_hi:[1,0]
	v_pk_mul_f32 v[70:71], v[70:71], v[150:151] op_sel_hi:[1,0]
	v_pk_mul_f32 v[56:57], v[56:57], v[150:151] op_sel_hi:[1,0]
	v_pk_mul_f32 v[58:59], v[58:59], v[150:151] op_sel_hi:[1,0]
	v_pk_mul_f32 v[44:45], v[44:45], v[150:151] op_sel_hi:[1,0]
	v_pk_mul_f32 v[46:47], v[46:47], v[150:151] op_sel_hi:[1,0]
	v_pk_mul_f32 v[36:37], v[36:37], v[150:151] op_sel_hi:[1,0]
	v_pk_mul_f32 v[38:39], v[38:39], v[150:151] op_sel_hi:[1,0]
	v_pk_mul_f32 v[60:61], v[60:61], v[150:151] op_sel_hi:[1,0]
	v_pk_mul_f32 v[62:63], v[62:63], v[150:151] op_sel_hi:[1,0]
	v_pk_mul_f32 v[90:91], v[90:91], v[152:153] op_sel_hi:[1,0]
	v_pk_mul_f32 v[88:89], v[88:89], v[152:153] op_sel_hi:[1,0]
	v_pk_mul_f32 v[82:83], v[82:83], v[152:153] op_sel_hi:[1,0]
	v_pk_mul_f32 v[80:81], v[80:81], v[152:153] op_sel_hi:[1,0]
	v_pk_mul_f32 v[74:75], v[74:75], v[152:153] op_sel_hi:[1,0]
	v_pk_mul_f32 v[72:73], v[72:73], v[152:153] op_sel_hi:[1,0]
	v_pk_mul_f32 v[66:67], v[66:67], v[152:153] op_sel_hi:[1,0]
	v_pk_mul_f32 v[64:65], v[64:65], v[152:153] op_sel_hi:[1,0]
	v_pk_mul_f32 v[54:55], v[54:55], v[152:153] op_sel_hi:[1,0]
	v_pk_mul_f32 v[52:53], v[52:53], v[152:153] op_sel_hi:[1,0]
	v_pk_mul_f32 v[42:43], v[42:43], v[152:153] op_sel_hi:[1,0]
	v_pk_mul_f32 v[40:41], v[40:41], v[152:153] op_sel_hi:[1,0]
	v_pk_mul_f32 v[34:35], v[34:35], v[152:153] op_sel_hi:[1,0]
	v_pk_mul_f32 v[32:33], v[32:33], v[152:153] op_sel_hi:[1,0]
	v_pk_mul_f32 v[50:51], v[50:51], v[152:153] op_sel_hi:[1,0]
	v_pk_mul_f32 v[48:49], v[48:49], v[152:153] op_sel_hi:[1,0]
	s_branch .LBB0_321

; template <int MODE> ...
;   int tid = threadIdx.x;
;   asm volatile("" : "+v"(tid));
;   const int lane = tid & 63, c = lane & 15, quad = lane >> 4;
;   float m_run[2] = {-1e30f, -1e30f}, l_run[2] = {0.f, 0.f};
; #pragma unroll
;   for (int qs = 0; qs < 2; ++qs)
; #pragma unroll
;     for (int i = 0; i < 8; ++i) o[qs][i] = (f32x4){0.f, 0.f, 0.f, 0.f};
;   const int krow0 = tid >> 4, kch = tid & 15;
;   const int vrow0 = tid >> 3, vch = tid & 7;
;   const bf16_t* kp = Kg + (size_t)(jlo * 64 + krow0) * NPAD + kch * 8;
;   const bf16_t* vp0 = VTg + (size_t)vrow0 * SEQ + jlo * 64 + vch * 8;
;   uint4 kr0 = *(const uint4*)kp, kr1 = *(const uint4*)(kp + (size_t)32 * NPAD);
;   uint4 vr0 = *(const uint4*)vp0, vr1 = *(const uint4*)(vp0 + (size_t)64 * SEQ);
;   __syncthreads();
;   stage_write_k((bf16_t*)smem, krow0, kch, kr0, kr1);
;   stage_write_v((bf16_t*)(smem + KT_BYTES), vrow0, vch, vr0, vr1);
;   __syncthreads();
; __device__ __forceinline__ void attn_phase(const bf16_t* __restrict__ proj, const bf16_t* __restrict__ KC,
;                            const bf16_t* __restrict__ VCT, const bf16_t* __restrict__ VT,
;                            bf16_t* __restrict__ mixed) {
;     ...
;     bf16x8 qf[2][4];
; #pragma unroll
;     for (int qs = 0; qs < 2; ++qs) {
;       const bf16_t* qp = proj + (row0 + qs * 4) * NPAD + OFF_Q + head * 128 + quad * 8;
; #pragma unroll
;       for (int ks = 0; ks < 4; ++ks) qf[qs][ks] = *(const bf16x8*)(qp + ks * 32);
;     }
.LBB0_655:
	v_mov_b64_e32 v[0:1], s[28:29]
	v_mad_u64_u32 v[192:193], s[6:7], v184, s81, v[0:1]
	v_mad_i32_i24 v193, v185, s81, v193
	s_mul_i32 s6, s26, 0x7a00
	v_mov_b32_e32 v105, v181
	v_lshl_add_u64 v[0:1], v[192:193], 0, v[180:181]
	s_add_u32 s62, s28, s6
	v_lshl_add_u64 v[16:17], v[0:1], 0, v[104:105]
	s_addc_u32 s63, s29, 0
	s_lshl_b32 s7, s71, 8
	v_add_co_u32_e32 v8, vcc, s19, v16
	s_add_u32 s8, s62, s7
	s_nop 0
	v_addc_co_u32_e32 v9, vcc, 0, v17, vcc
	s_addc_u32 s9, s63, 0
	v_add_co_u32_e32 v24, vcc, s85, v16
	s_add_u32 s8, s8, 0x5800
	v_lshl_add_u64 v[12:13], v[16:17], 0, s[42:43]
	v_lshl_add_u64 v[28:29], v[16:17], 0, s[46:47]
	v_addc_co_u32_e32 v25, vcc, 0, v17, vcc
	s_addc_u32 s9, s9, 0
	s_lshl_b32 s10, s95, 20
	v_mov_b32_e32 v39, v254
	global_load_dwordx4 v[0:3], v[12:13], off offset:64
	global_load_dwordx4 v[4:7], v[12:13], off offset:128
	s_nop 0
	global_load_dwordx4 v[8:11], v[8:9], off
	s_nop 0
	global_load_dwordx4 v[12:15], v[12:13], off offset:192
	s_nop 0
	global_load_dwordx4 v[16:19], v[28:29], off offset:64
	global_load_dwordx4 v[20:23], v[28:29], off offset:128
	s_nop 0
	global_load_dwordx4 v[24:27], v[24:25], off offset:2048
	s_nop 0
	global_load_dwordx4 v[28:31], v[28:29], off offset:192
	s_and_b32 s10, s10, 0x700000
	v_mov_b64_e32 v[32:33], s[8:9]
	v_and_b32_e32 v172, 15, v39
	v_ashrrev_i32_e32 v38, 4, v39
	v_ashrrev_i32_e32 v56, 3, v39
	s_add_u32 s14, s75, s10
	v_mad_i64_i32 v[34:35], s[8:9], v38, s81, v[32:33]
	v_lshlrev_b32_e32 v32, 4, v172
	v_mov_b32_e32 v33, v181
	v_ashrrev_i32_e32 v57, 31, v56
	s_addc_u32 s15, s76, 0
	v_and_b32_e32 v36, 7, v39
	v_lshl_add_u64 v[48:49], v[34:35], 0, v[32:33]
	v_lshlrev_b64 v[34:35], 13, v[56:57]
	v_lshl_add_u64 v[40:41], s[14:15], 0, v[34:35]
	v_lshlrev_b32_e32 v36, 4, v36
	v_mov_b32_e32 v37, v181
	v_lshl_add_u64 v[52:53], v[40:41], 0, v[36:37]
	global_load_dwordx4 v[40:43], v[52:53], off
	global_load_dwordx4 v[44:47], v[48:49], off
	v_add_co_u32_e32 v48, vcc, s89, v48
	v_bfe_u32 v166, v39, 4, 2
	s_nop 0
	v_addc_co_u32_e32 v49, vcc, 0, v49, vcc
	global_load_dwordx4 v[48:51], v[48:49], off
	v_add_co_u32_e32 v52, vcc, s88, v52
	v_lshlrev_b32_e32 v57, 3, v39
	s_nop 0
	v_addc_co_u32_e32 v53, vcc, 0, v53, vcc
	global_load_dwordx4 v[52:55], v[52:53], off
	v_lshlrev_b32_e32 v58, 4, v39
	v_lshlrev_b32_e32 v39, 1, v39
	v_and_b32_e32 v57, 32, v57
	v_and_b32_e32 v58, 16, v58
	v_and_b32_e32 v39, 4, v39
	v_mul_lo_u32 v59, v38, s86
	v_mul_lo_u32 v56, v56, s87
	v_or3_b32 v39, v57, v58, v39
	v_lshlrev_b32_e32 v168, 1, v59
	v_lshlrev_b32_e32 v169, 1, v56
	v_lshlrev_b32_e32 v170, 1, v39
	v_add3_u32 v56, 16, v168, v32
	v_add3_u32 v39, 16, v169, v170
	s_cmp_lg_u32 s96, 0
	v_lshlrev_b32_e32 v167, 4, v166
	v_add_u32_e32 v57, 0x4000, v39
	v_add_u32_e32 v39, 0x6800, v39
	s_barrier
	s_waitcnt vmcnt(1)
	ds_write_b128 v56, v[48:51] offset:8704
	ds_write_b128 v56, v[44:47]
	ds_write2_b64 v57, v[40:41], v[42:43] offset0:128 offset1:130
	s_waitcnt vmcnt(0)
	ds_write2_b64 v39, v[52:53], v[54:55] offset1:2
	s_waitcnt lgkmcnt(0)
	s_barrier
	s_cbranch_scc0 .LBB0_663
	s_add_u32 s6, s7, s6
	v_mad_i64_i32 v[38:39], s[8:9], v38, s81, 0
	s_addc_u32 s7, 0, 0
	v_lshl_add_u64 v[38:39], s[6:7], 0, v[38:39]
	s_and_b32 s6, s95, 7
	s_lshl_b32 s26, s6, 20
	v_lshlrev_b32_e32 v40, 3, v172
	v_lshl_add_u64 v[144:145], v[38:39], 0, v[32:33]
	v_lshl_add_u64 v[32:33], s[26:27], 0, v[34:35]
	v_mov_b32_e32 v34, v181
	v_mov_b32_e32 v35, v181
	v_lshl_add_u64 v[146:147], v[32:33], 0, v[36:37]
	v_mov_b32_e32 v32, v181
	v_mov_b32_e32 v33, v181
	v_mov_b32_e32 v164, 0xf149f2ca
	v_lshlrev_b32_e32 v175, 1, v40
	v_mov_b64_e32 v[42:43], v[34:35]
	v_mov_b64_e32 v[50:51], v[34:35]
	v_mov_b64_e32 v[58:59], v[34:35]
	v_mov_b64_e32 v[66:67], v[34:35]
	v_mov_b64_e32 v[74:75], v[34:35]
	v_mov_b64_e32 v[82:83], v[34:35]
	v_mov_b64_e32 v[90:91], v[34:35]
	v_mov_b64_e32 v[38:39], v[34:35]
	v_mov_b64_e32 v[46:47], v[34:35]
	v_mov_b64_e32 v[54:55], v[34:35]
	v_mov_b64_e32 v[62:63], v[34:35]
	v_mov_b64_e32 v[70:71], v[34:35]
	v_mov_b64_e32 v[78:79], v[34:35]
	v_mov_b64_e32 v[86:87], v[34:35]
	v_mov_b64_e32 v[94:95], v[34:35]
	v_mul_u32_u24_e32 v171, 0x110, v172
	v_mul_u32_u24_e32 v173, 0x90, v172
	v_add_u32_e32 v174, 16, v167
	v_mov_b32_e32 v194, v181
	v_mov_b32_e32 v195, v181
	s_mov_b64 s[60:61], 0
	v_mov_b64_e32 v[40:41], v[32:33]
	v_mov_b64_e32 v[48:49], v[32:33]
	v_mov_b64_e32 v[56:57], v[32:33]
	v_mov_b64_e32 v[64:65], v[32:33]
	v_mov_b64_e32 v[72:73], v[32:33]
	v_mov_b64_e32 v[80:81], v[32:33]
	v_mov_b64_e32 v[88:89], v[32:33]
	v_mov_b64_e32 v[36:37], v[32:33]
	v_mov_b64_e32 v[44:45], v[32:33]
	v_mov_b64_e32 v[52:53], v[32:33]
	v_mov_b64_e32 v[60:61], v[32:33]
	v_mov_b64_e32 v[68:69], v[32:33]
	v_mov_b64_e32 v[76:77], v[32:33]
	v_mov_b64_e32 v[84:85], v[32:33]
	v_mov_b64_e32 v[92:93], v[32:33]
	v_mov_b32_e32 v165, v164
	v_lshl_add_u64 v[144:145], s[24:25], 0, v[144:145]
	v_lshl_add_u64 v[146:147], s[24:25], 0, v[146:147]
	v_add_co_u32_e32 v144, vcc, s90, v144
	s_nop 1
	v_addc_co_u32_e32 v145, vcc, 0, v145, vcc
	v_add_co_u32_e32 v146, vcc, 0x3a800000, v146
	s_nop 1
	v_addc_co_u32_e32 v147, vcc, 0, v147, vcc
	s_branch .LBB0_659

; template <int MODE> ...
;     ...
;     if (j < jhi) {
;       kp += (size_t)64 * NPAD;
;       vp0 += 64;
;       kr0 = *(const uint4*)kp;
;       kr1 = *(const uint4*)(kp + (size_t)32 * NPAD);
;       vr0 = *(const uint4*)vp0;
;       vr1 = *(const uint4*)(vp0 + (size_t)64 * SEQ);
;     }
;     bool need = true;
;     if (MODE == 0) need = (wunion >> j) & 1ull;
;     if (need) {
;       f32x4 s[2][4];
; #pragma unroll
;       for (int mt = 0; mt < 4; ++mt) {
;         s[0][mt] = (f32x4){0.f, 0.f, 0.f, 0.f};
;         s[1][mt] = (f32x4){0.f, 0.f, 0.f, 0.f};
;       }
; #pragma unroll
;       for (int ks = 0; ks < 4; ++ks)
; #pragma unroll
;         for (int mt = 0; mt < 4; ++mt) {
;           bf16x8 a = *(const bf16x8*)(Kt + (mt * 16 + c) * KT_STRIDE + ks * 32 + quad * 8);
;           s[0][mt] = __builtin_amdgcn_mfma_f32_16x16x32_bf16(a, qf[0][ks], s[0][mt], 0, 0, 0);
;           s[1][mt] = __builtin_amdgcn_mfma_f32_16x16x32_bf16(a, qf[1][ks], s[1][mt], 0, 0, 0);
;         }
;       const bool edge = (j == jhi) || (MODE == 1 && j == jhi - 8);
;       bf16x8 pb[2][2];
;       if (edge) {
; #pragma unroll
;         for (int qs = 0; qs < 2; ++qs) {
;           const int key0 = j * 64 + quad * 4;
;           const int tk = tok[qs];
; #pragma unroll
;           for (int mt = 0; mt < 4; ++mt)
; #pragma unroll
;             for (int jj = 0; jj < 4; ++jj) {
;               const int key = key0 + mt * 16 + jj;
;               bool valid = key <= tk;
;               if (MODE == 1) valid = valid && (key > tk - 512);
;               s[qs][mt][jj] = valid ? s[qs][mt][jj] : RAW_MASKED;
;             }
;         }
;       }
;       float alpha[2];
; #pragma unroll
;       for (int qs = 0; qs < 2; ++qs) {
;         const bool sel = (MODE == 1) ? true : (bool)((mymask[qs] >> j) & 1ull);
;         float mx4[4];
; #pragma unroll
;         for (int mt = 0; mt < 4; ++mt)
;           mx4[mt] = fmaxf(fmaxf(s[qs][mt][0], s[qs][mt][1]), fmaxf(s[qs][mt][2], s[qs][mt][3]));
;         float mx = fmaxf(fmaxf(mx4[0], mx4[1]), fmaxf(mx4[2], mx4[3]));
;         mx = sel ? mx * SCL : -1e30f;
;         mx = quad_max(mx);
;         const float m_new = (mx > m_run[qs] + RESCALE_THR) ? mx : m_run[qs];
;         alpha[qs] = __builtin_amdgcn_exp2f(m_run[qs] - m_new);
.LBB0_659:
	v_add_co_u32_e32 v100, vcc, 0xf4000, v144
	s_lshl_b64 s[10:11], 1, s60
	global_load_dwordx4 v[96:99], v[144:145], off offset:2048
	v_addc_co_u32_e32 v101, vcc, 0, v145, vcc
	v_add_co_u32_e32 v108, vcc, 0x80000, v146
	s_and_b32 s8, s60, 1
	global_load_dwordx4 v[100:103], v[100:101], off offset:2048
	v_addc_co_u32_e32 v109, vcc, 0, v147, vcc
	global_load_dwordx4 v[104:107], v[146:147], off offset:128
	global_load_dwordx4 v[108:111], v[108:109], off offset:128
	s_and_b64 s[6:7], s[10:11], s[16:17]
	s_cmp_eq_u64 s[6:7], 0
	s_cbranch_scc1 .LBB0_658
	s_mul_i32 s6, s8, 0x8c00
	v_add_u32_e32 v157, s6, v174
	v_add_u32_e32 v156, v157, v171
	ds_read_b128 v[112:115], v156
	ds_read_b128 v[148:151], v156 offset:64
	ds_read_b128 v[120:123], v156 offset:4352
	ds_read_b128 v[128:131], v156 offset:8704
	ds_read_b128 v[136:139], v156 offset:13056
	s_waitcnt lgkmcnt(4)
	v_mfma_f32_16x16x32_bf16 v[116:119], v[112:115], v[8:11], 0
	v_mfma_f32_16x16x32_bf16 v[112:115], v[112:115], v[24:27], 0
	s_waitcnt lgkmcnt(3)
	v_mfma_f32_16x16x32_bf16 v[116:119], v[148:151], v[0:3], v[116:119]
	v_mfma_f32_16x16x32_bf16 v[112:115], v[148:151], v[16:19], v[112:115]
	ds_read_b128 v[148:151], v156 offset:4416
	s_waitcnt lgkmcnt(3)
	v_mfma_f32_16x16x32_bf16 v[124:127], v[120:123], v[8:11], 0
	v_mfma_f32_16x16x32_bf16 v[120:123], v[120:123], v[24:27], 0
	s_waitcnt lgkmcnt(0)
	v_mfma_f32_16x16x32_bf16 v[124:127], v[148:151], v[0:3], v[124:127]
	v_mfma_f32_16x16x32_bf16 v[120:123], v[148:151], v[16:19], v[120:123]
	ds_read_b128 v[148:151], v156 offset:8768
	v_mfma_f32_16x16x32_bf16 v[132:135], v[128:131], v[8:11], 0
	v_mfma_f32_16x16x32_bf16 v[128:131], v[128:131], v[24:27], 0
	s_waitcnt lgkmcnt(0)
	v_mfma_f32_16x16x32_bf16 v[132:135], v[148:151], v[0:3], v[132:135]
	v_mfma_f32_16x16x32_bf16 v[128:131], v[148:151], v[16:19], v[128:131]
	ds_read_b128 v[148:151], v156 offset:13120
	v_mfma_f32_16x16x32_bf16 v[140:143], v[136:139], v[8:11], 0
	v_mfma_f32_16x16x32_bf16 v[136:139], v[136:139], v[24:27], 0
	s_waitcnt lgkmcnt(0)
	v_mfma_f32_16x16x32_bf16 v[140:143], v[148:151], v[0:3], v[140:143]
	v_mfma_f32_16x16x32_bf16 v[136:139], v[148:151], v[16:19], v[136:139]
	ds_read_b128 v[148:151], v156 offset:128
	s_waitcnt lgkmcnt(0)
	v_mfma_f32_16x16x32_bf16 v[116:119], v[148:151], v[4:7], v[116:119]
	v_mfma_f32_16x16x32_bf16 v[112:115], v[148:151], v[20:23], v[112:115]
	ds_read_b128 v[148:151], v156 offset:4480
	s_waitcnt lgkmcnt(0)
	v_mfma_f32_16x16x32_bf16 v[124:127], v[148:151], v[4:7], v[124:127]
	v_mfma_f32_16x16x32_bf16 v[120:123], v[148:151], v[20:23], v[120:123]
	ds_read_b128 v[148:151], v156 offset:8832
	s_waitcnt lgkmcnt(0)
	v_mfma_f32_16x16x32_bf16 v[152:155], v[148:151], v[4:7], v[132:135]
	v_mfma_f32_16x16x32_bf16 v[148:151], v[148:151], v[20:23], v[128:131]
	s_nop 2
	ds_read_b128 v[128:131], v156 offset:13184
	s_waitcnt lgkmcnt(0)
	v_mfma_f32_16x16x32_bf16 v[176:179], v[128:131], v[4:7], v[140:143]
	v_mfma_f32_16x16x32_bf16 v[196:199], v[128:131], v[20:23], v[136:139]
	ds_read_b128 v[128:131], v156 offset:192
	s_waitcnt lgkmcnt(0)
	v_mfma_f32_16x16x32_bf16 v[132:135], v[128:131], v[28:31], v[112:115]
	s_nop 2
	ds_read_b128 v[112:115], v156 offset:4544
	v_mfma_f32_16x16x32_bf16 v[136:139], v[128:131], v[12:15], v[116:119]
	s_nop 2
	ds_read_b128 v[116:119], v156 offset:13248
	s_waitcnt lgkmcnt(1)
	v_mfma_f32_16x16x32_bf16 v[140:143], v[112:115], v[12:15], v[124:127]
	v_mfma_f32_16x16x32_bf16 v[128:131], v[112:115], v[28:31], v[120:123]
	ds_read_b128 v[112:115], v156 offset:8896
	s_waitcnt lgkmcnt(0)
	v_mfma_f32_16x16x32_bf16 v[124:127], v[112:115], v[12:15], v[152:155]
	s_nop 3
	s_nop 2
	v_mfma_f32_16x16x32_bf16 v[112:115], v[112:115], v[28:31], v[148:151]
	v_mfma_f32_16x16x32_bf16 v[120:123], v[116:119], v[12:15], v[176:179]
	s_nop 0
	s_nop 0
	v_max_f32_e32 v150, v138, v139
	v_max_f32_e32 v151, v142, v143
	v_max_f32_e32 v152, v124, v125
	v_max_f32_e32 v153, v126, v127
	s_nop 1
	v_max_f32_e32 v154, v122, v123
	v_and_b32_e32 v149, s11, v163
	v_and_b32_e32 v148, s10, v162
	v_max3_f32 v154, v120, v121, v154
	v_max3_f32 v150, v136, v137, v150
	v_max3_f32 v151, v140, v141, v151
	v_cmp_eq_u64_e64 s[6:7], 0, v[148:149]
	v_max3_f32 v148, v152, v153, v154
	v_max3_f32 v148, v150, v151, v148
	v_mul_f32_e32 v148, 0x3e0293ee, v148
	v_cndmask_b32_e64 v148, v148, v214, s[6:7]
	v_mov_b32_e32 v149, v148
	v_mfma_f32_16x16x32_bf16 v[116:119], v[116:119], v[28:31], v[196:199]
	s_nop 0
	v_permlane16_swap_b32_e32 v148, v149
	v_max_f32_e32 v151, v134, v135
	v_max_f32_e32 v148, v148, v149
	v_max_f32_e32 v152, v130, v131
	v_mov_b32_e32 v149, v148
	v_max_f32_e32 v153, v112, v113
	s_nop 0
	v_permlane32_swap_b32_e32 v148, v149
	v_max_f32_e32 v154, v114, v115
	v_max_f32_e32 v156, v118, v118
	v_max_f32_e32 v155, v156, v119
	v_max_f32_e32 v150, v148, v149
	v_and_b32_e32 v149, s11, v161
	v_and_b32_e32 v148, s10, v160
	v_max3_f32 v155, v116, v117, v155
	v_max3_f32 v151, v132, v133, v151
	v_max3_f32 v152, v128, v129, v152
	v_cmp_eq_u64_e64 s[10:11], 0, v[148:149]
	v_max3_f32 v148, v153, v154, v155
	v_max3_f32 v148, v151, v152, v148
	v_mul_f32_e32 v148, 0x3e0293ee, v148
	v_cndmask_b32_e64 v148, v148, v214, s[10:11]
	v_mov_b32_e32 v149, v148
	s_nop 1
	v_permlane16_swap_b32_e32 v148, v149
	v_max_f32_e32 v148, v148, v149
	v_mov_b32_e32 v149, v148
	s_nop 1
	v_permlane32_swap_b32_e32 v148, v149
	v_max_f32_e32 v151, v148, v149
	v_pk_add_f32 v[148:149], v[164:165], s[48:49] op_sel_hi:[1,0]
	s_nop 0
	v_cmp_gt_f32_e32 vcc, v150, v148
	v_cmp_gt_f32_e64 s[12:13], v151, v149
	s_nop 0
	v_cndmask_b32_e32 v148, v164, v150, vcc
	v_cndmask_b32_e64 v149, v165, v151, s[12:13]
	v_pk_add_f32 v[150:151], v[164:165], v[148:149] neg_lo:[0,1] neg_hi:[0,1]
	s_nop 0
	v_exp_f32_e32 v150, v150
	v_exp_f32_e32 v151, v151
	v_cmp_neq_f32_e32 vcc, 1.0, v150
	v_cmp_neq_f32_e64 s[12:13], 1.0, v151
	s_or_b64 vcc, vcc, s[12:13]
	s_cbranch_vccz .LBB0_657
; template <int MODE> ...
;     ...
;       if (__ballot(alpha[0] != 1.0f || alpha[1] != 1.0f) != 0ull) {
; #pragma unroll
;         for (int qs = 0; qs < 2; ++qs)
; #pragma unroll
;           for (int dt = 0; dt < 8; ++dt) {
;             o[qs][dt][0] *= alpha[qs]; o[qs][dt][1] *= alpha[qs]; o[qs][dt][2] *= alpha[qs]; o[qs][dt][3] *= alpha[qs];
;           }
;       }
	v_mov_b32_e32 v152, v151
	v_pk_mul_f32 v[92:93], v[92:93], v[150:151] op_sel_hi:[1,0]
	v_pk_mul_f32 v[94:95], v[94:95], v[150:151] op_sel_hi:[1,0]
	v_pk_mul_f32 v[84:85], v[84:85], v[150:151] op_sel_hi:[1,0]
	v_pk_mul_f32 v[86:87], v[86:87], v[150:151] op_sel_hi:[1,0]
	v_pk_mul_f32 v[76:77], v[76:77], v[150:151] op_sel_hi:[1,0]
	v_pk_mul_f32 v[78:79], v[78:79], v[150:151] op_sel_hi:[1,0]
	v_pk_mul_f32 v[68:69], v[68:69], v[150:151] op_sel_hi:[1,0]
	v_pk_mul_f32 v[70:71], v[70:71], v[150:151] op_sel_hi:[1,0]
	v_pk_mul_f32 v[60:61], v[60:61], v[150:151] op_sel_hi:[1,0]
	v_pk_mul_f32 v[62:63], v[62:63], v[150:151] op_sel_hi:[1,0]
	v_pk_mul_f32 v[52:53], v[52:53], v[150:151] op_sel_hi:[1,0]
	v_pk_mul_f32 v[54:55], v[54:55], v[150:151] op_sel_hi:[1,0]
	v_pk_mul_f32 v[44:45], v[44:45], v[150:151] op_sel_hi:[1,0]
	v_pk_mul_f32 v[46:47], v[46:47], v[150:151] op_sel_hi:[1,0]
	v_pk_mul_f32 v[36:37], v[36:37], v[150:151] op_sel_hi:[1,0]
	v_pk_mul_f32 v[38:39], v[38:39], v[150:151] op_sel_hi:[1,0]
	v_pk_mul_f32 v[90:91], v[90:91], v[152:153] op_sel_hi:[1,0]
	v_pk_mul_f32 v[88:89], v[88:89], v[152:153] op_sel_hi:[1,0]
	v_pk_mul_f32 v[82:83], v[82:83], v[152:153] op_sel_hi:[1,0]
	v_pk_mul_f32 v[80:81], v[80:81], v[152:153] op_sel_hi:[1,0]
	v_pk_mul_f32 v[74:75], v[74:75], v[152:153] op_sel_hi:[1,0]
	v_pk_mul_f32 v[72:73], v[72:73], v[152:153] op_sel_hi:[1,0]
	v_pk_mul_f32 v[66:67], v[66:67], v[152:153] op_sel_hi:[1,0]
	v_pk_mul_f32 v[64:65], v[64:65], v[152:153] op_sel_hi:[1,0]
	v_pk_mul_f32 v[58:59], v[58:59], v[152:153] op_sel_hi:[1,0]
	v_pk_mul_f32 v[56:57], v[56:57], v[152:153] op_sel_hi:[1,0]
	v_pk_mul_f32 v[50:51], v[50:51], v[152:153] op_sel_hi:[1,0]
	v_pk_mul_f32 v[48:49], v[48:49], v[152:153] op_sel_hi:[1,0]
	v_pk_mul_f32 v[42:43], v[42:43], v[152:153] op_sel_hi:[1,0]
	v_pk_mul_f32 v[40:41], v[40:41], v[152:153] op_sel_hi:[1,0]
	v_pk_mul_f32 v[34:35], v[34:35], v[152:153] op_sel_hi:[1,0]
	v_pk_mul_f32 v[32:33], v[32:33], v[152:153] op_sel_hi:[1,0]
	s_branch .LBB0_657
